# GEMM job prologue: second K-tile staging issued together with the first (before the first wait)
# baseline (speedup 1.0000x reference)
.LBB0_432:
	v_and_b32_e32 v15, 15, v8
	s_add_u32 s55, s46, s6
	v_and_b32_e32 v16, 48, v8
	v_lshlrev_b32_e32 v15, 6, v15
	v_lshlrev_b32_e32 v8, 2, v8
	s_addc_u32 s78, s47, s7
	v_or_b32_e32 v17, v15, v16
	s_lshl_b32 s4, s4, 13
	v_and_b32_e32 v8, 32, v8
	v_bitop3_b32 v15, v15, v8, v16 bitop3:0x36
	v_bitop3_b32 v8, v17, s4, v8 bitop3:0xde
	s_lshl_b32 s4, s5, 12
	s_and_b32 s4, s4, 0x3000
	v_or_b32_e32 v166, s4, v15
	s_mov_b64 s[4:5], 0x80
	s_add_i32 m0, s21, 0x18000
	v_lshl_add_u64 v[6:7], v[6:7], 0, s[4:5]
	global_load_lds_dwordx4 v[6:7], off
	v_lshl_add_u64 v[4:5], v[4:5], 0, s[4:5]
	s_add_i32 m0, s21, 0x1a000
	s_add_i32 s79, s21, 0x8000
	global_load_lds_dwordx4 v[4:5], off
	v_lshl_add_u64 v[0:1], v[0:1], 0, s[4:5]
	s_mov_b32 m0, s79
	s_add_i32 s80, s21, 0xa000
	global_load_lds_dwordx4 v[0:1], off
	v_lshl_add_u64 v[0:1], v[2:3], 0, s[4:5]
	s_add_u32 s4, s0, 0x40080
	s_mov_b32 m0, s80
	s_addc_u32 s5, s1, 0
	global_load_lds_dwordx4 v[0:1], off
	s_add_i32 m0, s21, 0x1c000
	v_lshl_add_u64 v[0:1], s[4:5], 0, v[176:177]
	global_load_lds_dwordx4 v[0:1], off
	v_lshl_add_u64 v[0:1], s[4:5], 0, v[156:157]
	s_add_i32 m0, s21, 0x1e000
	s_cmpk_lt_u32 s8, 0x100
	global_load_lds_dwordx4 v[0:1], off
	s_waitcnt vmcnt(8)
	s_barrier
	s_cselect_b64 s[34:35], -1, 0
	s_ashr_i32 s4, s26, 31
	s_lshr_b32 s4, s4, 29
	s_add_i32 s4, s26, s4
	s_ashr_i32 s82, s4, 3
	s_and_b32 s4, s4, -8
	s_sub_i32 s83, s26, s4
	v_readlane_b32 s4, v249, 30
	s_ashr_i32 s81, s72, 31
	s_add_i32 s84, s82, 1
	s_lshl_b32 s85, s4, 3
	s_cmp_lg_u32 s9, 2
	s_cselect_b64 s[40:41], -1, 0
	s_cmp_lg_u32 s9, 3
	s_cselect_b64 s[42:43], -1, 0
	s_cmp_eq_u32 s9, 1
	s_cselect_b64 s[44:45], -1, 0
	s_abs_i32 s87, s85
	v_cvt_f32_u32_e32 v0, s87
	s_abs_i32 s91, s74
	s_bfe_i32 s86, s4, 0x1001c
	s_sub_i32 s4, 0, s87
	v_rcp_iflag_f32_e32 v0, v0
	v_and_b32_e32 v1, 1, v9
	s_waitcnt vmcnt(6)
	s_mov_b32 s88, 0
	v_mul_f32_e32 v0, 0x4f7ffffe, v0
	v_cvt_u32_f32_e32 v0, v0
	s_ashr_i32 s90, s74, 31
	v_mov_b32_e32 v159, v177
	v_mov_b32_e32 v161, v177
	v_readfirstlane_b32 s5, v0
	v_cvt_f32_u32_e32 v0, s91
	s_mul_i32 s4, s4, s5
	s_mul_hi_u32 s4, s5, s4
	s_add_i32 s89, s5, s4
	v_rcp_iflag_f32_e32 v0, v0
	s_sub_i32 s4, 0, s91
	v_add_u32_e32 v167, 0, v8
	s_mov_b64 s[46:47], s[2:3]
	v_mul_f32_e32 v0, 0x4f7ffffe, v0
	v_cvt_u32_f32_e32 v0, v0
	s_mov_b64 s[48:49], s[0:1]
	s_mov_b32 s10, 0x800000
	s_movk_i32 s11, 0x2000
	v_readfirstlane_b32 s5, v0
	v_lshlrev_b32_e32 v0, 14, v9
	v_and_b32_e32 v0, 0xffff8000, v0
	v_lshl_add_u32 v0, v10, 11, v0
	v_lshl_or_b32 v0, v1, 6, v0
	v_lshl_add_u32 v158, v11, 1, v0
	v_lshlrev_b32_e32 v0, 14, v12
	v_and_b32_e32 v0, 0xffff8000, v0
	s_mul_i32 s4, s4, s5
	v_lshl_add_u32 v0, v13, 11, v0
	v_and_b32_e32 v1, 1, v12
	s_mul_hi_u32 s4, s5, s4
	v_lshl_or_b32 v0, v1, 6, v0
	s_add_i32 s92, s5, s4
	v_lshl_add_u32 v160, v14, 1, v0
	s_mov_b32 s64, 0xff61b1e6
	s_barrier
	s_branch .LBB0_435

.LBB0_505:
	s_add_u32 s83, s46, s2
	s_addc_u32 s84, s47, s3
	s_add_i32 m0, s79, 0x18000
	v_lshl_add_u64 v[0:1], v[0:1], 0, s[44:45]
	global_load_lds_dwordx4 v[0:1], off
	v_lshl_add_u64 v[0:1], v[2:3], 0, s[44:45]
	s_add_i32 m0, s79, 0x1a000
	s_add_i32 s85, s79, 0x8000
	global_load_lds_dwordx4 v[0:1], off
	v_lshl_add_u64 v[0:1], v[8:9], 0, s[44:45]
	s_mov_b32 m0, s85
	s_add_i32 s86, s79, 0xa000
	global_load_lds_dwordx4 v[0:1], off
	v_lshl_add_u64 v[0:1], v[10:11], 0, s[44:45]
	s_mov_b32 m0, s86
	v_and_b32_e32 v19, 15, v12
	global_load_lds_dwordx4 v[0:1], off
	s_add_i32 m0, s79, 0x1c000
	v_lshl_add_u64 v[0:1], v[4:5], 0, s[44:45]
	global_load_lds_dwordx4 v[0:1], off
	v_lshl_add_u64 v[0:1], v[6:7], 0, s[44:45]
	s_add_i32 m0, s79, 0x1e000
	v_and_b32_e32 v20, 48, v12
	global_load_lds_dwordx4 v[0:1], off
	s_waitcnt vmcnt(8)
	s_barrier
	v_lshlrev_b32_e32 v19, 6, v19
	v_lshlrev_b32_e32 v12, 2, v12
	v_or_b32_e32 v21, v19, v20
	s_lshl_b32 s0, s0, 13
	v_and_b32_e32 v12, 32, v12
	v_bitop3_b32 v19, v19, v12, v20 bitop3:0x36
	v_bitop3_b32 v12, v21, s0, v12 bitop3:0xde
	s_lshl_b32 s0, s1, 12
	s_and_b32 s0, s0, 0x3000
	s_cmpk_lt_u32 s9, 0x100
	s_cselect_b64 s[44:45], -1, 0
	s_abs_i32 s89, s74
	v_cvt_f32_u32_e32 v0, s89
	s_abs_i32 s93, s61
	v_or_b32_e32 v149, s0, v19
	s_sub_i32 s0, 0, s89
	v_rcp_iflag_f32_e32 v0, v0
	v_and_b32_e32 v1, 1, v13
	s_waitcnt vmcnt(6)
	s_ashr_i32 s87, s72, 31
	v_mul_f32_e32 v0, 0x4f7ffffe, v0
	v_cvt_u32_f32_e32 v0, v0
	s_ashr_i32 s88, s74, 31
	s_mov_b32 s90, 0
	s_ashr_i32 s92, s61, 31
	v_readfirstlane_b32 s1, v0
	v_cvt_f32_u32_e32 v0, s93
	s_mul_i32 s0, s0, s1
	s_mul_hi_u32 s0, s1, s0
	s_add_i32 s91, s1, s0
	v_rcp_iflag_f32_e32 v0, v0
	s_sub_i32 s0, 0, s93
	v_mov_b32_e32 v141, v177
	v_mov_b32_e32 v143, v177
	v_mul_f32_e32 v0, 0x4f7ffffe, v0
	v_cvt_u32_f32_e32 v0, v0
	v_add_u32_e32 v150, 0, v12
	s_mov_b64 s[2:3], s[4:5]
	s_barrier
	v_readfirstlane_b32 s1, v0
	v_lshlrev_b32_e32 v0, 14, v13
	v_and_b32_e32 v0, 0xffff8000, v0
	v_lshl_add_u32 v0, v14, 11, v0
	v_lshl_or_b32 v0, v1, 6, v0
	v_lshl_add_u32 v140, v15, 1, v0
	v_lshlrev_b32_e32 v0, 14, v16
	v_and_b32_e32 v0, 0xffff8000, v0
	s_mul_i32 s0, s0, s1
	v_lshl_add_u32 v0, v17, 11, v0
	v_and_b32_e32 v1, 1, v16
	s_mul_hi_u32 s0, s1, s0
	v_lshl_or_b32 v0, v1, 6, v0
	s_add_i32 s94, s1, s0
	v_lshl_add_u32 v142, v18, 1, v0
	s_mov_b64 s[0:1], s[36:37]
	s_branch .LBB0_508

.LBB0_560:
	v_and_b32_e32 v15, 15, v8
	s_add_u32 s86, s46, s36
	v_and_b32_e32 v16, 48, v8
	v_lshlrev_b32_e32 v15, 6, v15
	v_lshlrev_b32_e32 v8, 2, v8
	s_addc_u32 s87, s47, s37
	v_or_b32_e32 v17, v15, v16
	s_lshl_b32 s4, s4, 13
	v_and_b32_e32 v8, 32, v8
	v_bitop3_b32 v15, v15, v8, v16 bitop3:0x36
	v_bitop3_b32 v8, v17, s4, v8 bitop3:0xde
	s_lshl_b32 s4, s5, 12
	s_add_i32 m0, s33, 0x18000
	v_lshl_add_u64 v[6:7], v[6:7], 0, s[44:45]
	s_and_b32 s4, s4, 0x3000
	global_load_lds_dwordx4 v[6:7], off
	v_lshl_add_u64 v[4:5], v[4:5], 0, s[44:45]
	s_add_i32 m0, s33, 0x1a000
	s_add_i32 s88, s33, 0x8000
	s_add_i32 s89, s33, 0xa000
	v_or_b32_e32 v161, s4, v15
	global_load_lds_dwordx4 v[4:5], off
	v_lshl_add_u64 v[0:1], v[0:1], 0, s[44:45]
	s_mov_b32 m0, s88
	s_add_u32 s4, s48, 0x40080
	global_load_lds_dwordx4 v[0:1], off
	v_lshl_add_u64 v[0:1], v[2:3], 0, s[44:45]
	s_mov_b32 m0, s89
	s_addc_u32 s5, s49, 0
	global_load_lds_dwordx4 v[0:1], off
	s_add_i32 m0, s33, 0x1c000
	v_lshl_add_u64 v[0:1], s[4:5], 0, v[146:147]
	global_load_lds_dwordx4 v[0:1], off
	v_lshl_add_u64 v[0:1], s[4:5], 0, v[150:151]
	s_add_i32 m0, s33, 0x1e000
	s_cmpk_lt_u32 s8, 0x100
	global_load_lds_dwordx4 v[0:1], off
	s_waitcnt vmcnt(8)
	s_barrier
	s_cselect_b64 s[36:37], -1, 0
	s_abs_i32 s92, s74
	v_cvt_f32_u32_e32 v0, s92
	s_abs_i32 s96, s61
	s_sub_i32 s4, 0, s92
	s_waitcnt vmcnt(6)
	v_rcp_iflag_f32_e32 v0, v0
	s_ashr_i32 s90, s72, 31
	s_ashr_i32 s91, s74, 31
	s_mov_b32 s93, 0
	v_mul_f32_e32 v0, 0x4f7ffffe, v0
	v_cvt_u32_f32_e32 v0, v0
	s_ashr_i32 s95, s61, 31
	s_lshl_b32 s54, s61, 4
	v_add_u32_e32 v163, 0, v8
	v_readfirstlane_b32 s5, v0
	v_cvt_f32_u32_e32 v0, s96
	s_mul_i32 s4, s4, s5
	s_mul_hi_u32 s4, s5, s4
	s_add_i32 s94, s5, s4
	v_rcp_iflag_f32_e32 v0, v0
	s_sub_i32 s4, 0, s96
	s_mov_b64 s[44:45], s[6:7]
	s_mov_b64 s[46:47], s[48:49]
	v_mul_f32_e32 v0, 0x4f7ffffe, v0
	v_cvt_u32_f32_e32 v0, v0
	s_barrier
	v_readfirstlane_b32 s5, v0
	v_add_u32_e32 v0, v14, v12
	s_mul_i32 s4, s4, s5
	v_add_lshl_u32 v176, v0, v13, 1
	v_add_u32_e32 v0, v11, v9
	s_mul_hi_u32 s4, s5, s4
	v_lshl_add_u64 v[152:153], s[0:1], 0, v[176:177]
	v_add_lshl_u32 v176, v0, v10, 1
	s_add_i32 s97, s5, s4
	v_lshl_add_u64 v[154:155], s[0:1], 0, v[176:177]
	s_branch .LBB0_563

.LBB0_613:
	s_lshl_b32 s4, s4, 12
	s_and_b32 s33, s4, 0x3000
	s_mov_b64 s[4:5], 0x80
	s_add_i32 m0, s21, 0x18000
	v_lshl_add_u64 v[6:7], v[6:7], 0, s[4:5]
	global_load_lds_dwordx4 v[6:7], off
	v_lshl_add_u64 v[4:5], v[4:5], 0, s[4:5]
	s_add_i32 m0, s21, 0x1a000
	s_add_i32 s78, s21, 0x8000
	s_lshl_b32 s1, s1, 13
	global_load_lds_dwordx4 v[4:5], off
	v_lshl_add_u64 v[0:1], v[0:1], 0, s[4:5]
	s_mov_b32 m0, s78
	s_add_i32 s79, s21, 0xa000
	global_load_lds_dwordx4 v[0:1], off
	v_lshl_add_u64 v[0:1], v[2:3], 0, s[4:5]
	s_add_u32 s4, s6, 0x40080
	s_mov_b32 m0, s79
	s_addc_u32 s5, s7, 0
	global_load_lds_dwordx4 v[0:1], off
	s_add_i32 m0, s21, 0x1c000
	v_lshl_add_u64 v[0:1], s[4:5], 0, v[162:163]
	global_load_lds_dwordx4 v[0:1], off
	v_lshl_add_u64 v[0:1], s[4:5], 0, v[166:167]
	s_add_i32 m0, s21, 0x1e000
	s_cmpk_lt_u32 s8, 0x100
	global_load_lds_dwordx4 v[0:1], off
	s_waitcnt vmcnt(8)
	s_barrier
	s_cselect_b64 s[34:35], -1, 0
	s_ashr_i32 s4, s26, 31
	s_lshr_b32 s4, s4, 29
	s_add_i32 s4, s26, s4
	s_ashr_i32 s64, s4, 3
	s_and_b32 s4, s4, -8
	v_readlane_b32 s10, v249, 30
	s_ashr_i32 s60, s72, 31
	s_sub_i32 s65, s26, s4
	s_add_i32 s57, s64, 1
	s_lshl_b32 s66, s10, 3
	s_cmp_lg_u32 s11, 2
	s_cselect_b64 s[40:41], -1, 0
	s_cmp_lg_u32 s11, 3
	s_cselect_b64 s[42:43], -1, 0
	s_cmp_eq_u32 s11, 1
	s_cselect_b64 s[44:45], -1, 0
	s_lshl_b32 s4, s9, 7
	s_ashr_i32 s5, s4, 31
	v_readlane_b32 s80, v250, 26
	s_lshl_b64 s[4:5], s[4:5], 2
	v_readlane_b32 s86, v250, 32
	v_readlane_b32 s87, v250, 33
	s_add_u32 s67, s86, s4
	s_addc_u32 s68, s87, s5
	s_lshl_b32 s8, s9, 8
	v_readlane_b32 s81, v250, 27
	s_ashr_i32 s9, s8, 31
	s_lshl_b64 s[8:9], s[8:9], 1
	v_readlane_b32 s80, v253, 53
	v_readlane_b32 s81, v253, 54
	s_add_u32 s46, s80, s8
	v_readlane_b32 s90, v250, 36
	s_addc_u32 s47, s81, s9
	v_readlane_b32 s88, v250, 34
	v_readlane_b32 s89, v250, 35
	v_readlane_b32 s91, v250, 37
	s_add_u32 s69, s90, s4
	s_addc_u32 s88, s91, s5
	s_abs_i32 s89, s66
	v_cvt_f32_u32_e32 v3, s89
	v_and_b32_e32 v15, 15, v8
	v_lshlrev_b32_e32 v2, 2, v8
	v_and_b32_e32 v16, 48, v8
	v_lshlrev_b32_e32 v0, 6, v15
	v_and_b32_e32 v2, 32, v2
	v_or_b32_e32 v1, v0, v16
	v_bitop3_b32 v0, v0, v2, v16 bitop3:0x36
	v_or_b32_e32 v194, s33, v0
	v_rcp_iflag_f32_e32 v0, v3
	s_abs_i32 s91, s74
	v_bitop3_b32 v1, v1, s1, v2 bitop3:0xde
	v_cvt_f32_u32_e32 v2, s91
	v_mul_f32_e32 v0, 0x4f7ffffe, v0
	v_cvt_u32_f32_e32 v0, v0
	s_sub_i32 s1, 0, s89
	v_rcp_iflag_f32_e32 v2, v2
	v_readlane_b32 s93, v250, 39
	v_readfirstlane_b32 s4, v0
	s_mul_i32 s1, s1, s4
	v_mul_f32_e32 v0, 0x4f7ffffe, v2
	v_cvt_u32_f32_e32 v0, v0
	s_mul_hi_u32 s1, s4, s1
	s_add_i32 s93, s4, s1
	v_and_b32_e32 v2, 1, v9
	v_readfirstlane_b32 s4, v0
	v_lshlrev_b32_e32 v0, 14, v9
	v_and_b32_e32 v0, 0xffff8000, v0
	v_lshl_add_u32 v0, v10, 11, v0
	v_lshl_or_b32 v0, v2, 6, v0
	v_lshl_add_u32 v168, v11, 1, v0
	v_lshlrev_b32_e32 v0, 14, v12
	s_sub_i32 s1, 0, s91
	v_and_b32_e32 v0, 0xffff8000, v0
	s_waitcnt vmcnt(6)
	s_mul_i32 s1, s1, s4
	v_lshl_add_u32 v0, v13, 11, v0
	v_and_b32_e32 v2, 1, v12
	v_readlane_b32 s92, v250, 38
	v_readlane_b32 s94, v250, 40
	v_readlane_b32 s95, v250, 41
	s_mul_hi_u32 s1, s4, s1
	v_lshl_or_b32 v0, v2, 6, v0
	s_bfe_i32 s90, s10, 0x1001c
	s_mov_b32 s92, 0
	s_ashr_i32 s94, s74, 31
	s_add_i32 s95, s4, s1
	v_mov_b32_e32 v169, v177
	v_lshl_add_u32 v170, v14, 1, v0
	v_mov_b32_e32 v171, v177
	v_add_u32_e32 v195, 0, v1
	s_mov_b64 s[48:49], s[2:3]
	s_mov_b64 s[50:51], s[6:7]
	s_mov_b32 s10, 0x800000
	s_movk_i32 s11, 0x2000
	s_mov_b32 s70, 0xbfb8aa3b
	s_mov_b32 s77, 0x3f317217
	v_readlane_b32 s82, v250, 28
	v_readlane_b32 s83, v250, 29
	v_readlane_b32 s84, v250, 30
	v_readlane_b32 s85, v250, 31
	s_barrier
	s_branch .LBB0_616

.LBB0_988:
	v_and_b32_e32 v19, 15, v12
	v_and_b32_e32 v20, 48, v12
	v_lshlrev_b32_e32 v12, 2, v12
	v_lshlrev_b32_e32 v19, 6, v19
	v_and_b32_e32 v12, 32, v12
	s_lshl_b32 s0, s0, 12
	v_or_b32_e32 v21, v19, v20
	s_lshl_b32 s1, s1, 13
	v_bitop3_b32 v19, v19, v12, v20 bitop3:0x36
	s_and_b32 s0, s0, 0x3000
	v_bitop3_b32 v12, v21, s1, v12 bitop3:0xde
	v_or_b32_e32 v213, s0, v19
	s_mov_b64 s[0:1], 0x80
	s_add_i32 m0, s23, 0x18000
	v_lshl_add_u64 v[0:1], v[0:1], 0, s[0:1]
	global_load_lds_dwordx4 v[0:1], off
	v_lshl_add_u64 v[0:1], v[2:3], 0, s[0:1]
	s_add_i32 m0, s23, 0x1a000
	s_add_i32 s81, s23, 0x8000
	global_load_lds_dwordx4 v[0:1], off
	v_lshl_add_u64 v[0:1], v[8:9], 0, s[0:1]
	s_mov_b32 m0, s81
	s_add_i32 s82, s23, 0xa000
	global_load_lds_dwordx4 v[0:1], off
	v_lshl_add_u64 v[0:1], v[10:11], 0, s[0:1]
	s_mov_b32 m0, s82
	s_lshr_b32 s80, s4, 6
	global_load_lds_dwordx4 v[0:1], off
	s_add_i32 m0, s23, 0x1c000
	v_lshl_add_u64 v[0:1], v[4:5], 0, s[0:1]
	global_load_lds_dwordx4 v[0:1], off
	v_lshl_add_u64 v[0:1], v[6:7], 0, s[0:1]
	s_add_i32 m0, s23, 0x1e000
	s_add_i32 s33, s80, -2
	global_load_lds_dwordx4 v[0:1], off
	s_waitcnt vmcnt(8)
	s_barrier
	s_cmpk_lt_u32 s8, 0x100
	s_cselect_b64 s[40:41], -1, 0
	s_ashr_i32 s0, s26, 31
	s_lshr_b32 s0, s0, 29
	s_add_i32 s0, s26, s0
	s_ashr_i32 s84, s0, 3
	s_and_b32 s0, s0, -8
	s_sub_i32 s85, s26, s0
	v_readlane_b32 s0, v249, 30
	s_ashr_i32 s83, s72, 31
	s_add_i32 s86, s84, 1
	s_lshl_b32 s87, s0, 3
	s_cmp_lg_u32 s2, 2
	s_cselect_b64 s[42:43], -1, 0
	s_cmp_lg_u32 s2, 3
	s_cselect_b64 s[44:45], -1, 0
	s_cmp_eq_u32 s2, 1
	s_cselect_b64 s[46:47], -1, 0
	s_abs_i32 s89, s87
	v_cvt_f32_u32_e32 v0, s89
	s_abs_i32 s93, s74
	s_bfe_i32 s88, s0, 0x1001c
	s_sub_i32 s0, 0, s89
	v_rcp_iflag_f32_e32 v0, v0
	s_waitcnt vmcnt(6)
	s_mov_b32 s13, s12
	s_mov_b32 s48, s12
	v_mul_f32_e32 v0, 0x4f7ffffe, v0
	v_cvt_u32_f32_e32 v0, v0
	s_mov_b32 s49, s12
	s_mov_b32 s90, 0
	s_ashr_i32 s92, s74, 31
	v_readfirstlane_b32 s1, v0
	v_cvt_f32_u32_e32 v0, s93
	s_mul_i32 s0, s0, s1
	s_mul_hi_u32 s0, s1, s0
	s_add_i32 s91, s1, s0
	v_rcp_iflag_f32_e32 v0, v0
	s_sub_i32 s0, 0, s93
	v_add_u32_e32 v214, 0, v12
	s_mov_b64 s[2:3], s[6:7]
	v_mul_f32_e32 v0, 0x4f7ffffe, v0
	v_cvt_u32_f32_e32 v0, v0
	s_movk_i32 s57, 0x2000
	s_barrier
	v_readfirstlane_b32 s1, v0
	s_mul_i32 s0, s0, s1
	s_mul_hi_u32 s0, s1, s0
	v_add_u32_e32 v0, v15, v13
	s_add_i32 s94, s1, s0
	v_add_lshl_u32 v176, v0, v14, 1
	s_mov_b64 s[0:1], s[10:11]
	v_add_u32_e32 v0, v18, v16
	v_lshl_add_u64 v[192:193], s[0:1], 0, v[176:177]
	v_add_lshl_u32 v176, v0, v17, 1
	v_lshl_add_u64 v[194:195], s[0:1], 0, v[176:177]
	s_mov_b64 s[0:1], s[36:37]
	s_branch .LBB0_991

.LBB0_1062:
	v_and_b32_e32 v15, 15, v8
	s_add_u32 s42, s46, s36
	v_and_b32_e32 v16, 48, v8
	v_lshlrev_b32_e32 v15, 6, v15
	v_lshlrev_b32_e32 v8, 2, v8
	s_addc_u32 s43, s47, s37
	v_or_b32_e32 v17, v15, v16
	s_lshl_b32 s4, s4, 13
	v_and_b32_e32 v8, 32, v8
	v_bitop3_b32 v15, v15, v8, v16 bitop3:0x36
	v_bitop3_b32 v8, v17, s4, v8 bitop3:0xde
	s_lshl_b32 s4, s5, 12
	s_add_i32 m0, s79, 0x18000
	v_lshl_add_u64 v[6:7], v[6:7], 0, s[44:45]
	s_and_b32 s4, s4, 0x3000
	global_load_lds_dwordx4 v[6:7], off
	v_lshl_add_u64 v[4:5], v[4:5], 0, s[44:45]
	s_add_i32 m0, s79, 0x1a000
	s_add_i32 s83, s79, 0x8000
	s_add_i32 s84, s79, 0xa000
	v_or_b32_e32 v173, s4, v15
	global_load_lds_dwordx4 v[4:5], off
	v_lshl_add_u64 v[0:1], v[0:1], 0, s[44:45]
	s_mov_b32 m0, s83
	s_add_u32 s4, s2, 0x40080
	global_load_lds_dwordx4 v[0:1], off
	v_lshl_add_u64 v[0:1], v[2:3], 0, s[44:45]
	s_mov_b32 m0, s84
	s_addc_u32 s5, s3, 0
	global_load_lds_dwordx4 v[0:1], off
	s_add_i32 m0, s79, 0x1c000
	v_lshl_add_u64 v[0:1], s[4:5], 0, v[146:147]
	global_load_lds_dwordx4 v[0:1], off
	v_lshl_add_u64 v[0:1], s[4:5], 0, v[150:151]
	s_add_i32 m0, s79, 0x1e000
	s_cmpk_lt_u32 s9, 0x100
	global_load_lds_dwordx4 v[0:1], off
	s_waitcnt vmcnt(8)
	s_barrier
	s_cselect_b64 s[44:45], -1, 0
	s_abs_i32 s87, s74
	v_cvt_f32_u32_e32 v0, s87
	v_and_b32_e32 v1, 1, v9
	s_sub_i32 s4, 0, s87
	s_waitcnt vmcnt(6)
	v_rcp_iflag_f32_e32 v0, v0
	s_ashr_i32 s85, s72, 31
	s_ashr_i32 s86, s74, 31
	s_mov_b32 s88, 0
	v_mul_f32_e32 v0, 0x4f7ffffe, v0
	v_cvt_u32_f32_e32 v0, v0
	v_mov_b32_e32 v153, v177
	v_mov_b32_e32 v155, v177
	v_add_u32_e32 v175, 0, v8
	v_readfirstlane_b32 s5, v0
	v_lshlrev_b32_e32 v0, 14, v9
	v_and_b32_e32 v0, 0xffff8000, v0
	v_lshl_add_u32 v0, v10, 11, v0
	v_lshl_or_b32 v0, v1, 6, v0
	v_lshl_add_u32 v152, v11, 1, v0
	v_lshlrev_b32_e32 v0, 14, v12
	v_and_b32_e32 v0, 0xffff8000, v0
	s_mul_i32 s4, s4, s5
	v_lshl_add_u32 v0, v13, 11, v0
	v_and_b32_e32 v1, 1, v12
	s_mul_hi_u32 s4, s5, s4
	v_lshl_or_b32 v0, v1, 6, v0
	s_add_i32 s89, s5, s4
	v_lshl_add_u32 v154, v14, 1, v0
	s_mov_b64 s[46:47], s[0:1]
	s_mov_b64 s[48:49], s[2:3]
	s_barrier
	s_branch .LBB0_1065

.LBB0_1115:
	s_add_u32 s81, s46, s10
	v_and_b32_e32 v19, 15, v12
	v_and_b32_e32 v20, 48, v12
	v_lshlrev_b32_e32 v12, 2, v12
	s_addc_u32 s82, s47, s11
	v_lshlrev_b32_e32 v19, 6, v19
	v_and_b32_e32 v12, 32, v12
	s_lshl_b32 s4, s4, 12
	v_or_b32_e32 v21, v19, v20
	s_lshl_b32 s5, s5, 13
	v_bitop3_b32 v19, v19, v12, v20 bitop3:0x36
	s_and_b32 s4, s4, 0x3000
	v_bitop3_b32 v12, v21, s5, v12 bitop3:0xde
	v_or_b32_e32 v139, s4, v19
	s_mov_b64 s[4:5], 0x80
	s_add_i32 m0, s9, 0x18000
	v_lshl_add_u64 v[0:1], v[0:1], 0, s[4:5]
	global_load_lds_dwordx4 v[0:1], off
	v_lshl_add_u64 v[0:1], v[2:3], 0, s[4:5]
	s_add_i32 m0, s9, 0x1a000
	s_add_i32 s83, s9, 0x8000
	global_load_lds_dwordx4 v[0:1], off
	v_lshl_add_u64 v[0:1], v[8:9], 0, s[4:5]
	s_mov_b32 m0, s83
	s_add_i32 s84, s9, 0xa000
	global_load_lds_dwordx4 v[0:1], off
	v_lshl_add_u64 v[0:1], v[10:11], 0, s[4:5]
	s_mov_b32 m0, s84
	s_lshr_b32 s77, s25, 6
	global_load_lds_dwordx4 v[0:1], off
	s_add_i32 m0, s9, 0x1c000
	v_lshl_add_u64 v[0:1], v[4:5], 0, s[4:5]
	global_load_lds_dwordx4 v[0:1], off
	v_lshl_add_u64 v[0:1], v[6:7], 0, s[4:5]
	s_add_i32 m0, s9, 0x1e000
	s_add_i32 s85, s77, -2
	global_load_lds_dwordx4 v[0:1], off
	s_waitcnt vmcnt(8)
	s_barrier
	s_cmpk_lt_u32 s34, 0x100
	s_cselect_b64 s[34:35], -1, 0
	s_abs_i32 s88, s74
	v_cvt_f32_u32_e32 v0, s88
	s_sub_i32 s4, 0, s88
	v_mov_b32_e32 v1, v177
	s_waitcnt vmcnt(6)
	v_rcp_iflag_f32_e32 v0, v0
	s_ashr_i32 s86, s72, 31
	s_ashr_i32 s87, s74, 31
	s_mov_b32 s89, 0
	v_mul_f32_e32 v0, 0x4f7ffffe, v0
	v_cvt_u32_f32_e32 v0, v0
	v_add_u32_e32 v140, 0, v12
	s_mov_b64 s[38:39], s[44:45]
	s_mov_b64 s[40:41], s[42:43]
	v_readfirstlane_b32 s5, v0
	v_add_u32_e32 v0, v15, v13
	v_add_lshl_u32 v0, v0, v14, 1
	s_mul_i32 s4, s4, s5
	v_lshl_add_u64 v[134:135], s[22:23], 0, v[0:1]
	v_add_u32_e32 v0, v18, v16
	s_mul_hi_u32 s4, s5, s4
	v_add_lshl_u32 v0, v0, v17, 1
	s_add_i32 s90, s5, s4
	v_lshl_add_u64 v[136:137], s[22:23], 0, v[0:1]
	s_barrier
	s_branch .LBB0_1118
